# v18 plus one static s_setprio 2 for waves 4-7 during the attention phases instead of per-stage flips
# baseline (speedup 1.0000x reference)
; #define LAS __attribute__((address_space(3)))
; __device__ __forceinline__ void attn2_unit(bf16_t* Z, const bf16_t* Hb, const float* rc, const float* rs, LAS unsigned char* lds, int b, int h, int qblk) {
;     const int tid = threadIdx.x, lane = tid & 63, wave = __builtin_amdgcn_readfirstlane(tid >> 6);
;     const int l31 = lane & 31, hi = lane >> 5, l15 = lane & 15;
;     const size_t rowb = (size_t)b * SEQ;
;     const int q0 = qblk * 256 + wave * 32, cw = q0 >> 6, npairs = qblk * 2 + 2;
;     bf16x8 qf[6];
;     { const bf16_t* qp = Hb + (rowb + q0 + l31) * 1024 + h * 96 + 8 * hi;
; #pragma unroll
;         for (int s = 0; s < 6; ++s) qf[s] = *(const bf16x8*)(qp + 16 * s);
;         const int pos = q0 + l31;
; #pragma unroll
;         for (int s = 4; s < 6; ++s) { const u32x4 raw = __builtin_bit_cast(u32x4, qf[s]); const int i0 = 8 * (s - 4) + 4 * hi;
;             const f32x4 c = *(const f32x4*)(rc + pos * 16 + i0), sn = *(const f32x4*)(rs + pos * 16 + i0);
;             u32x4 o;
;             { const float x1 = bflo(raw.x), x2 = bfhi(raw.x); o.x = cvtpk2(x1 * c[0] - x2 * sn[0], x2 * c[0] + x1 * sn[0]); }
;             { const float x1 = bflo(raw.y), x2 = bfhi(raw.y); o.y = cvtpk2(x1 * c[1] - x2 * sn[1], x2 * c[1] + x1 * sn[1]); }
;             { const float x1 = bflo(raw.z), x2 = bfhi(raw.z); o.z = cvtpk2(x1 * c[2] - x2 * sn[2], x2 * c[2] + x1 * sn[2]); }
; template <int ph>
; __device__ __forceinline__ void run_phase(const Params& p, unsigned char* lds, const int vc, const LnRows lnl) {
;     ...
;             } else if (sp == 5 && PHON(5)) {
;                 const float* rc = (const float*)(ws + WS_ROPE); const float* rs = rc + SEQ * 16;
;                 if (G == 256) {
;                     const int x = bx & 7, j = bx >> 3;
;                     for (int r = 0; r < 2; ++r) { const int bh = 4 * x + 2 * r + (j >> 4), pp = j & 15;
;                         attn2_unit(Z, Hb, rc, rs, ldsl, bh >> 3, bh & 7, 31 - pp);
;                         attn2_unit(Z, Hb, rc, rs, ldsl, bh >> 3, bh & 7, pp); }
;                 } else {
;                     for (int w = bx; w < 512; w += G) { const int bh = w >> 4, pp = w & 15;
;                         attn2_unit(Z, Hb, rc, rs, ldsl, bh >> 3, bh & 7, 31 - pp);
;                         attn2_unit(Z, Hb, rc, rs, ldsl, bh >> 3, bh & 7, pp); }
;                 }
.LBB0_690:
	s_cmp_lt_i32 s4, 7
	s_cselect_b64 s[0:1], -1, 0
	s_cmp_gt_i32 s5, 6
	s_cselect_b64 s[2:3], -1, 0
	s_and_b64 s[0:1], s[0:1], s[2:3]
	s_andn2_b64 vcc, exec, s[0:1]
	s_cbranch_vccnz .LBB0_937
	s_add_u32 s0, s96, 0x4c00000
	s_addc_u32 s1, s97, 0
	s_add_u32 s2, s96, 0x8c00000
	s_addc_u32 s3, s97, 0
	s_add_u32 s4, s96, 0x100000
	s_addc_u32 s5, s97, 0
	s_add_u32 s14, s96, 0x180000
	s_addc_u32 s15, s97, 0
	v_readfirstlane_b32 s6, v192
	s_nop 3
	s_cmp_ge_u32 s6, 0x100
	s_cbranch_scc0 .Lattn_prio_1
	s_setprio 2
.Lattn_prio_1:
	s_cmpk_eq_i32 s88, 0x100
	s_mov_b64 s[6:7], -1
	s_cbranch_scc1 .LBB0_788
	s_cmpk_gt_i32 s67, 0x1ff
	s_cbranch_scc1 .LBB0_787
	v_bfe_u32 v0, v192, 5, 1
	v_lshlrev_b32_e32 v2, 3, v0
	v_lshlrev_b32_e32 v4, 2, v0
	v_lshlrev_b32_e32 v156, 4, v0
	v_lshrrev_b32_e32 v0, 2, v192
	v_lshlrev_b32_e32 v3, 3, v192
	v_and_or_b32 v0, v0, 3, v4
	v_and_b32_e32 v154, 24, v3
	v_lshlrev_b32_e32 v195, 6, v0
	v_and_b32_e32 v0, 16, v192
	v_lshlrev_b32_e32 v3, 2, v192
	v_and_or_b32 v0, v3, 12, v0
	v_lshlrev_b32_e32 v218, 1, v0
	v_mbcnt_lo_u32_b32 v0, -1, 0
	v_mbcnt_hi_u32_b32 v0, -1, v0
	v_and_b32_e32 v5, 64, v0
	v_xor_b32_e32 v3, 32, v0
	v_add_u32_e32 v5, 64, v5
	v_cmp_lt_i32_e32 vcc, v3, v5
	v_mov_b32_e32 v1, 0
	v_and_b32_e32 v152, 31, v192
	v_cndmask_b32_e32 v0, v0, v3, vcc
	v_lshlrev_b32_e32 v219, 2, v0
	v_and_b32_e32 v0, 3, v192
	v_lshlrev_b32_e32 v0, 4, v0
	v_mov_b32_e32 v157, v1
	v_lshl_add_u64 v[6:7], s[96:97], 0, v[0:1]
	s_mov_b64 s[6:7], 0x8d60400
	v_lshlrev_b32_e32 v164, 1, v2
	v_and_b32_e32 v153, 63, v192
	v_mul_u32_u24_e32 v155, 0xd0, v152
	s_mov_b32 s17, 0
	v_lshl_add_u64 v[158:159], s[4:5], 0, v[156:157]
	v_lshl_add_u64 v[160:161], s[14:15], 0, v[156:157]
	v_lshl_add_u64 v[162:163], v[6:7], 0, s[6:7]
	v_mov_b32_e32 v166, v164
	v_mov_b32_e32 v167, v1
	s_mov_b32 s9, 0x4ec4ec4f
	s_mov_b64 s[18:19], 0x580
	s_movk_i32 s13, 0x2c00
	s_mov_b64 s[20:21], 0xc00
	s_mov_b64 s[22:23], 0x400
	s_mov_b32 s42, 0x41000000
	s_mov_b64 s[26:27], 0x160000
	v_lshlrev_b32_e32 v168, 1, v4
	v_mov_b32_e32 v157, 0x2c00
	s_mov_b32 s43, s67
	s_mov_b32 s46, s67
	s_branch .LBB0_695

; #define LAS __attribute__((address_space(3)))
; __device__ __forceinline__ void a2_qk(const LAS unsigned char* kb, const bf16x8 (&qf)[6], const f32x16& cneg, f32x16& st0, f32x16& st1) {
;     { const bf16x8 a0 = *(const LAS bf16x8*)(kb), a1 = *(const LAS bf16x8*)(kb + 32 * AT_KROW);
;       st0 = __builtin_amdgcn_mfma_f32_32x32x16_bf16(a0, qf[0], cneg, 0, 0, 0); st1 = __builtin_amdgcn_mfma_f32_32x32x16_bf16(a1, qf[0], cneg, 0, 0, 0); }
; #pragma unroll
;     for (int s = 1; s < 6; ++s) { const bf16x8 a0 = *(const LAS bf16x8*)(kb + s * 32), a1 = *(const LAS bf16x8*)(kb + 32 * AT_KROW + s * 32);
;         st0 = __builtin_amdgcn_mfma_f32_32x32x16_bf16(a0, qf[s], st0, 0, 0, 0); st1 = __builtin_amdgcn_mfma_f32_32x32x16_bf16(a1, qf[s], st1, 0, 0, 0); }
; }
; __device__ __forceinline__ float a2_max(const f32x16& st0, const f32x16& st1) {
;     float mt = fmaxf(st0[0], st1[0]);
; #pragma unroll
;     for (int r = 1; r < 16; ++r) mt = fmaxf(fmaxf(mt, st0[r]), st1[r]);
;     return fmaxf(mt, __shfl_xor(mt, 32));
; }
; __device__ __forceinline__ void attn2_unit(bf16_t* Z, const bf16_t* Hb, const float* rc, const float* rs, LAS unsigned char* lds, int b, int h, int qblk) {
;     ...
;         if (2 * kp + 1 <= cw) {
;             f32x16 sa0, sa1, sb0, sb1; bf16x8 pa[4], pb[4];
;             __builtin_amdgcn_s_setprio(1);
;             a2_qk(kb, qf, cneg, sa0, sa1);
;             a2_qk(kb + 64 * AT_KROW, qf, cneg, sb0, sb1);
;             __builtin_amdgcn_s_setprio(0);
;             const float mt = fmaxf(a2_max(sa0, sa1), a2_max(sb0, sb1));
;             if (kp == 0 || __builtin_amdgcn_ballot_w64(mt > 8.f) != 0ull) {
.LBB0_824:
	s_andn2_b64 vcc, exec, s[6:7]
	s_cbranch_vccnz .LBB0_833
	v_add_u32_e32 v0, v3, v156
	ds_read_b128 v[4:7], v0
	ds_read_b128 v[8:11], v0 offset:32
	v_mov_b64_e32 v[94:95], v[62:63]
	v_mov_b64_e32 v[92:93], v[60:61]
	v_mov_b64_e32 v[90:91], v[58:59]
	s_waitcnt lgkmcnt(0)
	v_mfma_f32_32x32x16_bf16 v[112:127], v[4:7], v[128:131], v[48:63]
	ds_read_b128 v[4:7], v0 offset:6656
	ds_read_b128 v[12:15], v0 offset:6688
	v_mov_b64_e32 v[88:89], v[56:57]
	v_mov_b64_e32 v[86:87], v[54:55]
	v_mov_b64_e32 v[84:85], v[52:53]
	v_mov_b64_e32 v[82:83], v[50:51]
	v_mov_b64_e32 v[80:81], v[48:49]
	s_waitcnt lgkmcnt(0)
	v_mfma_f32_32x32x16_bf16 v[96:111], v[4:7], v[128:131], v[48:63]
	v_mfma_f32_32x32x16_bf16 v[112:127], v[8:11], v[132:135], v[112:127]
	ds_read_b128 v[4:7], v0 offset:64
	ds_read_b128 v[8:11], v0 offset:96
	v_mfma_f32_32x32x16_bf16 v[96:111], v[12:15], v[132:135], v[96:111]
	s_waitcnt lgkmcnt(0)
	v_mfma_f32_32x32x16_bf16 v[112:127], v[4:7], v[136:139], v[112:127]
	ds_read_b128 v[4:7], v0 offset:6720
	ds_read_b128 v[12:15], v0 offset:6752
	s_waitcnt lgkmcnt(0)
	v_mfma_f32_32x32x16_bf16 v[96:111], v[4:7], v[136:139], v[96:111]
	v_mfma_f32_32x32x16_bf16 v[112:127], v[8:11], v[140:143], v[112:127]
	ds_read_b128 v[4:7], v0 offset:128
	ds_read_b128 v[8:11], v0 offset:160
	v_mfma_f32_32x32x16_bf16 v[96:111], v[12:15], v[140:143], v[96:111]
	s_waitcnt lgkmcnt(0)
	v_mfma_f32_32x32x16_bf16 v[112:127], v[4:7], v[144:147], v[112:127]
	ds_read_b128 v[4:7], v0 offset:6784
	ds_read_b128 v[12:15], v0 offset:6816
	s_waitcnt lgkmcnt(0)
	v_mfma_f32_32x32x16_bf16 v[96:111], v[4:7], v[144:147], v[96:111]
	v_mfma_f32_32x32x16_bf16 v[112:127], v[8:11], v[148:151], v[112:127]
	ds_read_b128 v[4:7], v0 offset:13312
	ds_read_b128 v[8:11], v0 offset:13344
	s_waitcnt lgkmcnt(0)
	v_mfma_f32_32x32x16_bf16 v[64:79], v[4:7], v[128:131], v[48:63]
	ds_read_b128 v[4:7], v0 offset:19968
	v_mfma_f32_32x32x16_bf16 v[96:111], v[12:15], v[148:151], v[96:111]
	ds_read_b128 v[12:15], v0 offset:20000
	s_waitcnt lgkmcnt(0)
	v_mfma_f32_32x32x16_bf16 v[80:95], v[4:7], v[128:131], v[80:95]
	v_mfma_f32_32x32x16_bf16 v[64:79], v[8:11], v[132:135], v[64:79]
	ds_read_b128 v[4:7], v0 offset:13376
	ds_read_b128 v[8:11], v0 offset:13408
	v_mfma_f32_32x32x16_bf16 v[80:95], v[12:15], v[132:135], v[80:95]
	s_waitcnt lgkmcnt(0)
	v_mfma_f32_32x32x16_bf16 v[64:79], v[4:7], v[136:139], v[64:79]
	ds_read_b128 v[4:7], v0 offset:20032
	ds_read_b128 v[12:15], v0 offset:20064
	s_waitcnt lgkmcnt(0)
	v_mfma_f32_32x32x16_bf16 v[80:95], v[4:7], v[136:139], v[80:95]
	v_mfma_f32_32x32x16_bf16 v[64:79], v[8:11], v[140:143], v[64:79]
	ds_read_b128 v[4:7], v0 offset:13440
	ds_read_b128 v[8:11], v0 offset:13472
	v_mfma_f32_32x32x16_bf16 v[80:95], v[12:15], v[140:143], v[80:95]
	s_waitcnt lgkmcnt(0)
	v_mfma_f32_32x32x16_bf16 v[64:79], v[4:7], v[144:147], v[64:79]
	ds_read_b128 v[4:7], v0 offset:20096
	ds_read_b128 v[12:15], v0 offset:20128
	s_waitcnt lgkmcnt(0)
	v_mfma_f32_32x32x16_bf16 v[80:95], v[4:7], v[144:147], v[80:95]
	v_mfma_f32_32x32x16_bf16 v[64:79], v[8:11], v[148:151], v[64:79]
	v_mfma_f32_32x32x16_bf16 v[80:95], v[12:15], v[148:151], v[80:95]
	v_max_f32_e32 v0, v96, v96
	v_max_f32_e32 v3, v112, v112
	v_max_f32_e32 v0, v3, v0
	s_nop 7
	v_max_f32_e32 v3, v80, v80
	v_max_f32_e32 v4, v64, v64
	v_max_f32_e32 v3, v4, v3
	v_max3_f32 v3, v3, v65, v81
	v_max3_f32 v3, v3, v66, v82
	v_max3_f32 v0, v0, v113, v97
	v_max3_f32 v3, v3, v67, v83
	v_max3_f32 v0, v0, v114, v98
	v_max3_f32 v3, v3, v68, v84
	v_max3_f32 v0, v0, v115, v99
	v_max3_f32 v3, v3, v69, v85
	v_max3_f32 v0, v0, v116, v100
	v_max3_f32 v3, v3, v70, v86
	v_max3_f32 v0, v0, v117, v101
	v_max3_f32 v3, v3, v71, v87
	v_max3_f32 v0, v0, v118, v102
	v_max3_f32 v3, v3, v72, v88
	v_max3_f32 v0, v0, v119, v103
	v_max3_f32 v3, v3, v73, v89
	v_max3_f32 v0, v0, v120, v104
	v_max3_f32 v3, v3, v74, v90
	v_max3_f32 v0, v0, v121, v105
	v_max3_f32 v3, v3, v75, v91
	v_max3_f32 v0, v0, v122, v106
	v_max3_f32 v3, v3, v76, v92
	v_max3_f32 v0, v0, v123, v107
	v_max3_f32 v3, v3, v77, v93
	v_max3_f32 v0, v0, v124, v108
	v_max3_f32 v3, v3, v78, v94
	v_max3_f32 v3, v3, v79, v95
	v_max3_f32 v0, v0, v125, v109
	ds_bpermute_b32 v4, v219, v3
	v_max3_f32 v0, v0, v126, v110
	v_max3_f32 v0, v0, v127, v111
	ds_bpermute_b32 v5, v219, v0
	s_cmp_eq_u32 s65, 1
	s_waitcnt lgkmcnt(0)
	v_max_f32_e32 v4, v4, v4
	v_max_f32_e32 v3, v3, v4
	s_cselect_b64 s[34:35], -1, 0
	s_cmp_lg_u32 s65, 1
	v_max3_f32 v3, v0, v5, v3
	s_cbranch_scc0 .LBB0_835
	v_cmp_lt_f32_e32 vcc, s53, v3
	s_mov_b64 s[24:25], 0
	s_mov_b64 s[6:7], 0
	s_cbranch_vccz .LBB0_828
	v_max_f32_e32 v0, v3, v3
	v_max_f32_e32 v0, 0, v0
	s_mov_b64 s[6:7], -1

; #define LAS __attribute__((address_space(3)))
; __device__ __forceinline__ void a2_qk(const LAS unsigned char* kb, const bf16x8 (&qf)[6], const f32x16& cneg, f32x16& st0, f32x16& st1) {
;     { const bf16x8 a0 = *(const LAS bf16x8*)(kb), a1 = *(const LAS bf16x8*)(kb + 32 * AT_KROW);
;       st0 = __builtin_amdgcn_mfma_f32_32x32x16_bf16(a0, qf[0], cneg, 0, 0, 0); st1 = __builtin_amdgcn_mfma_f32_32x32x16_bf16(a1, qf[0], cneg, 0, 0, 0); }
; #pragma unroll
;     for (int s = 1; s < 6; ++s) { const bf16x8 a0 = *(const LAS bf16x8*)(kb + s * 32), a1 = *(const LAS bf16x8*)(kb + 32 * AT_KROW + s * 32);
;         st0 = __builtin_amdgcn_mfma_f32_32x32x16_bf16(a0, qf[s], st0, 0, 0, 0); st1 = __builtin_amdgcn_mfma_f32_32x32x16_bf16(a1, qf[s], st1, 0, 0, 0); }
; }
; __device__ __forceinline__ float a2_max(const f32x16& st0, const f32x16& st1) {
;     float mt = fmaxf(st0[0], st1[0]);
; #pragma unroll
;     for (int r = 1; r < 16; ++r) mt = fmaxf(fmaxf(mt, st0[r]), st1[r]);
;     return fmaxf(mt, __shfl_xor(mt, 32));
; }
; __device__ __forceinline__ void attn2_unit(bf16_t* Z, const bf16_t* Hb, const float* rc, const float* rs, LAS unsigned char* lds, int b, int h, int qblk) {
;     ...
;         if (2 * kp + 1 <= cw) {
;             f32x16 sa0, sa1, sb0, sb1; bf16x8 pa[4], pb[4];
;             __builtin_amdgcn_s_setprio(1);
;             a2_qk(kb, qf, cneg, sa0, sa1);
;             a2_qk(kb + 64 * AT_KROW, qf, cneg, sb0, sb1);
;             __builtin_amdgcn_s_setprio(0);
;             const float mt = fmaxf(a2_max(sa0, sa1), a2_max(sb0, sb1));
;             if (kp == 0 || __builtin_amdgcn_ballot_w64(mt > 8.f) != 0ull) {
.LBB0_870:
	s_andn2_b64 vcc, exec, s[6:7]
	s_cbranch_vccnz .LBB0_879
	v_add_u32_e32 v0, v3, v156
	ds_read_b128 v[4:7], v0
	ds_read_b128 v[8:11], v0 offset:32
	v_mov_b64_e32 v[94:95], v[62:63]
	v_mov_b64_e32 v[92:93], v[60:61]
	v_mov_b64_e32 v[90:91], v[58:59]
	s_waitcnt lgkmcnt(0)
	v_mfma_f32_32x32x16_bf16 v[112:127], v[4:7], v[128:131], v[48:63]
	ds_read_b128 v[4:7], v0 offset:6656
	ds_read_b128 v[12:15], v0 offset:6688
	v_mov_b64_e32 v[88:89], v[56:57]
	v_mov_b64_e32 v[86:87], v[54:55]
	v_mov_b64_e32 v[84:85], v[52:53]
	v_mov_b64_e32 v[82:83], v[50:51]
	v_mov_b64_e32 v[80:81], v[48:49]
	s_waitcnt lgkmcnt(0)
	v_mfma_f32_32x32x16_bf16 v[96:111], v[4:7], v[128:131], v[48:63]
	v_mfma_f32_32x32x16_bf16 v[112:127], v[8:11], v[132:135], v[112:127]
	ds_read_b128 v[4:7], v0 offset:64
	ds_read_b128 v[8:11], v0 offset:96
	v_mfma_f32_32x32x16_bf16 v[96:111], v[12:15], v[132:135], v[96:111]
	s_waitcnt lgkmcnt(0)
	v_mfma_f32_32x32x16_bf16 v[112:127], v[4:7], v[136:139], v[112:127]
	ds_read_b128 v[4:7], v0 offset:6720
	ds_read_b128 v[12:15], v0 offset:6752
	s_waitcnt lgkmcnt(0)
	v_mfma_f32_32x32x16_bf16 v[96:111], v[4:7], v[136:139], v[96:111]
	v_mfma_f32_32x32x16_bf16 v[112:127], v[8:11], v[140:143], v[112:127]
	ds_read_b128 v[4:7], v0 offset:128
	ds_read_b128 v[8:11], v0 offset:160
	v_mfma_f32_32x32x16_bf16 v[96:111], v[12:15], v[140:143], v[96:111]
	s_waitcnt lgkmcnt(0)
	v_mfma_f32_32x32x16_bf16 v[112:127], v[4:7], v[144:147], v[112:127]
	ds_read_b128 v[4:7], v0 offset:6784
	ds_read_b128 v[12:15], v0 offset:6816
	s_waitcnt lgkmcnt(0)
	v_mfma_f32_32x32x16_bf16 v[96:111], v[4:7], v[144:147], v[96:111]
	v_mfma_f32_32x32x16_bf16 v[112:127], v[8:11], v[148:151], v[112:127]
	ds_read_b128 v[4:7], v0 offset:13312
	ds_read_b128 v[8:11], v0 offset:13344
	s_waitcnt lgkmcnt(0)
	v_mfma_f32_32x32x16_bf16 v[64:79], v[4:7], v[128:131], v[48:63]
	ds_read_b128 v[4:7], v0 offset:19968
	v_mfma_f32_32x32x16_bf16 v[96:111], v[12:15], v[148:151], v[96:111]
	ds_read_b128 v[12:15], v0 offset:20000
	s_waitcnt lgkmcnt(0)
	v_mfma_f32_32x32x16_bf16 v[80:95], v[4:7], v[128:131], v[80:95]
	v_mfma_f32_32x32x16_bf16 v[64:79], v[8:11], v[132:135], v[64:79]
	ds_read_b128 v[4:7], v0 offset:13376
	ds_read_b128 v[8:11], v0 offset:13408
	v_mfma_f32_32x32x16_bf16 v[80:95], v[12:15], v[132:135], v[80:95]
	s_waitcnt lgkmcnt(0)
	v_mfma_f32_32x32x16_bf16 v[64:79], v[4:7], v[136:139], v[64:79]
	ds_read_b128 v[4:7], v0 offset:20032
	ds_read_b128 v[12:15], v0 offset:20064
	s_waitcnt lgkmcnt(0)
	v_mfma_f32_32x32x16_bf16 v[80:95], v[4:7], v[136:139], v[80:95]
	v_mfma_f32_32x32x16_bf16 v[64:79], v[8:11], v[140:143], v[64:79]
	ds_read_b128 v[4:7], v0 offset:13440
	ds_read_b128 v[8:11], v0 offset:13472
	v_mfma_f32_32x32x16_bf16 v[80:95], v[12:15], v[140:143], v[80:95]
	s_waitcnt lgkmcnt(0)
	v_mfma_f32_32x32x16_bf16 v[64:79], v[4:7], v[144:147], v[64:79]
	ds_read_b128 v[4:7], v0 offset:20096
	ds_read_b128 v[12:15], v0 offset:20128
	s_waitcnt lgkmcnt(0)
	v_mfma_f32_32x32x16_bf16 v[80:95], v[4:7], v[144:147], v[80:95]
	v_mfma_f32_32x32x16_bf16 v[64:79], v[8:11], v[148:151], v[64:79]
	v_mfma_f32_32x32x16_bf16 v[80:95], v[12:15], v[148:151], v[80:95]
	v_max_f32_e32 v0, v96, v96
	v_max_f32_e32 v3, v112, v112
	v_max_f32_e32 v0, v3, v0
	s_nop 7
	v_max_f32_e32 v3, v80, v80
	v_max_f32_e32 v4, v64, v64
	v_max_f32_e32 v3, v4, v3
	v_max3_f32 v3, v3, v65, v81
	v_max3_f32 v3, v3, v66, v82
	v_max3_f32 v0, v0, v113, v97
	v_max3_f32 v3, v3, v67, v83
	v_max3_f32 v0, v0, v114, v98
	v_max3_f32 v3, v3, v68, v84
	v_max3_f32 v0, v0, v115, v99
	v_max3_f32 v3, v3, v69, v85
	v_max3_f32 v0, v0, v116, v100
	v_max3_f32 v3, v3, v70, v86
	v_max3_f32 v0, v0, v117, v101
	v_max3_f32 v3, v3, v71, v87
	v_max3_f32 v0, v0, v118, v102
	v_max3_f32 v3, v3, v72, v88
	v_max3_f32 v0, v0, v119, v103
	v_max3_f32 v3, v3, v73, v89
	v_max3_f32 v0, v0, v120, v104
	v_max3_f32 v3, v3, v74, v90
	v_max3_f32 v0, v0, v121, v105
	v_max3_f32 v3, v3, v75, v91
	v_max3_f32 v0, v0, v122, v106
	v_max3_f32 v3, v3, v76, v92
	v_max3_f32 v0, v0, v123, v107
	v_max3_f32 v3, v3, v77, v93
	v_max3_f32 v0, v0, v124, v108
	v_max3_f32 v3, v3, v78, v94
	v_max3_f32 v3, v3, v79, v95
	v_max3_f32 v0, v0, v125, v109
	ds_bpermute_b32 v4, v219, v3
	v_max3_f32 v0, v0, v126, v110
	v_max3_f32 v0, v0, v127, v111
	ds_bpermute_b32 v5, v219, v0
	s_cmp_eq_u32 s35, 1
	s_waitcnt lgkmcnt(0)
	v_max_f32_e32 v4, v4, v4
	v_max_f32_e32 v3, v3, v4
	s_cselect_b64 s[28:29], -1, 0
	s_cmp_lg_u32 s35, 1
	v_max3_f32 v3, v0, v5, v3
	s_cbranch_scc0 .LBB0_881
	v_cmp_lt_f32_e32 vcc, s53, v3
	s_mov_b64 s[24:25], 0
	s_mov_b64 s[6:7], 0
	s_cbranch_vccz .LBB0_874
	v_max_f32_e32 v0, v3, v3
	v_max_f32_e32 v0, 0, v0
	s_mov_b64 s[6:7], -1

; __device__ __forceinline__ unsigned xb_ld(unsigned* p)              { return __hip_atomic_load(p, __ATOMIC_RELAXED, __HIP_MEMORY_SCOPE_AGENT); }
; __device__ __forceinline__ void xcd_barrier_complete(unsigned* bar, unsigned x, unsigned& nloc, unsigned& nx) {
;     const unsigned G = gridDim.x * gridDim.y * gridDim.z;
;     unsigned sum, cnt, mine, sp = 0u;
;     for (;;) {
;         sum = 0u; cnt = 0u; mine = 0u;
; #pragma unroll
;         for (unsigned j = 0; j < 16; ++j) { const unsigned c = xb_ld(&bar[XB_XCNT(j)]); sum += c; cnt += (c > 0u) ? 1u : 0u; mine = (j == x) ? c : mine; }
; __device__ __forceinline__ void xcd_barrier(const XcdBarrier& b) {
;     asm volatile("s_waitcnt vmcnt(0)" ::: "memory");
;     __syncthreads();
;     if (threadIdx.x == 0) {
;         unsigned* bar = b.bar;
;         __builtin_amdgcn_s_waitcnt(0);
;         unsigned nloc = b.st[0], nx = b.st[1];
;         if (nloc == 0u) { xcd_barrier_complete(bar, b.x, nloc, nx); b.st[0] = nloc; b.st[1] = nx; }
.LBB0_883:
	s_setprio 0
	v_readlane_b32 s4, v246, 12
	v_readlane_b32 s5, v246, 13
	s_cmp_lt_i32 s5, 8
	s_cbranch_scc1 .LBB0_937
	s_waitcnt vmcnt(0)
	s_waitcnt vmcnt(0)
	s_barrier
	s_mov_b64 s[0:1], exec
	v_readlane_b32 s2, v246, 10
	v_readlane_b32 s3, v246, 11
	s_and_b64 s[2:3], s[0:1], s[2:3]
	s_mov_b64 exec, s[2:3]
	s_cbranch_execz .LBB0_936
	s_add_i32 s2, 0, 0x23ff0
	v_mov_b32_e32 v0, s2
	s_waitcnt vmcnt(0) expcnt(0) lgkmcnt(0)
	ds_read_b32 v2, v0
	s_add_i32 s2, 0, 0x23ff4
	v_mov_b32_e32 v0, s2
	ds_read_b32 v0, v0
	s_waitcnt lgkmcnt(1)
	v_cmp_ne_u32_e32 vcc, 0, v2
	s_cbranch_vccnz .LBB0_900
	s_add_u32 s2, s96, 0x80200
	s_addc_u32 s3, s97, 0
	s_add_u32 s4, s96, 0x80400
	s_addc_u32 s5, s97, 0
	s_add_u32 s6, s96, 0x80500
	s_addc_u32 s7, s97, 0
	s_add_u32 s14, s96, 0x80600
	s_addc_u32 s15, s97, 0
	s_add_u32 s16, s96, 0x80700
	s_addc_u32 s17, s97, 0
	s_add_u32 s18, s96, 0x80800
	s_addc_u32 s19, s97, 0
	s_add_u32 s20, s96, 0x80900
	s_addc_u32 s21, s97, 0
	s_add_u32 s22, s96, 0x80a00
	s_addc_u32 s23, s97, 0
	s_add_u32 s24, s96, 0x80b00
	s_addc_u32 s25, s97, 0
	s_add_u32 s26, s96, 0x80c00
	s_addc_u32 s27, s97, 0
	s_add_u32 s28, s96, 0x80d00
	s_addc_u32 s29, s97, 0
	s_add_u32 s30, s96, 0x80e00
	s_addc_u32 s31, s97, 0
	s_add_u32 s34, s96, 0x80f00
	s_addc_u32 s35, s97, 0
	s_add_u32 s36, s96, 0x81000
	s_addc_u32 s37, s97, 0
	s_add_u32 s42, s96, 0x81100
	s_addc_u32 s43, s97, 0
	s_add_u32 s46, s96, 0x81200
	s_addc_u32 s47, s97, 0
	s_mul_i32 s9, s89, s84
	s_add_u32 s52, s96, 0x81300
	s_mul_i32 s9, s9, s88
	s_addc_u32 s53, s97, 0
	s_mov_b32 s13, 1
	v_mov_b32_e32 v16, 0
	s_branch .LBB0_888

; #define LAS __attribute__((address_space(3)))
; __device__ __forceinline__ void attn2_unit(bf16_t* Z, const bf16_t* Hb, const float* rc, const float* rs, LAS unsigned char* lds, int b, int h, int qblk) {
;     const int tid = threadIdx.x, lane = tid & 63, wave = __builtin_amdgcn_readfirstlane(tid >> 6);
;     const int l31 = lane & 31, hi = lane >> 5, l15 = lane & 15;
;     const size_t rowb = (size_t)b * SEQ;
;     const int q0 = qblk * 256 + wave * 32, cw = q0 >> 6, npairs = qblk * 2 + 2;
;     bf16x8 qf[6];
;     { const bf16_t* qp = Hb + (rowb + q0 + l31) * 1024 + h * 96 + 8 * hi;
; #pragma unroll
;         for (int s = 0; s < 6; ++s) qf[s] = *(const bf16x8*)(qp + 16 * s);
;         const int pos = q0 + l31;
; #pragma unroll
;         for (int s = 4; s < 6; ++s) { const u32x4 raw = __builtin_bit_cast(u32x4, qf[s]); const int i0 = 8 * (s - 4) + 4 * hi;
;             const f32x4 c = *(const f32x4*)(rc + pos * 16 + i0), sn = *(const f32x4*)(rs + pos * 16 + i0);
;             u32x4 o;
;             { const float x1 = bflo(raw.x), x2 = bfhi(raw.x); o.x = cvtpk2(x1 * c[0] - x2 * sn[0], x2 * c[0] + x1 * sn[0]); }
;             { const float x1 = bflo(raw.y), x2 = bfhi(raw.y); o.y = cvtpk2(x1 * c[1] - x2 * sn[1], x2 * c[1] + x1 * sn[1]); }
;             { const float x1 = bflo(raw.z), x2 = bfhi(raw.z); o.z = cvtpk2(x1 * c[2] - x2 * sn[2], x2 * c[2] + x1 * sn[2]); }
; template <int ph>
; __device__ __forceinline__ void run_phase(const Params& p, unsigned char* lds, const int vc, const LnRows lnl) {
;     ...
;             } else if (sp == 5 && PHON(5)) {
;                 const float* rc = (const float*)(ws + WS_ROPE); const float* rs = rc + SEQ * 16;
;                 if (G == 256) {
;                     const int x = bx & 7, j = bx >> 3;
;                     for (int r = 0; r < 2; ++r) { const int bh = 4 * x + 2 * r + (j >> 4), pp = j & 15;
;                         attn2_unit(Z, Hb, rc, rs, ldsl, bh >> 3, bh & 7, 31 - pp);
;                         attn2_unit(Z, Hb, rc, rs, ldsl, bh >> 3, bh & 7, pp); }
;                 } else {
;                     for (int w = bx; w < 512; w += G) { const int bh = w >> 4, pp = w & 15;
;                         attn2_unit(Z, Hb, rc, rs, ldsl, bh >> 3, bh & 7, 31 - pp);
;                         attn2_unit(Z, Hb, rc, rs, ldsl, bh >> 3, bh & 7, pp); }
;                 }
.LBB0_2101:
	s_cmp_lt_i32 s4, 18
	s_cselect_b64 s[0:1], -1, 0
	s_cmp_gt_i32 s5, 17
	s_cselect_b64 s[2:3], -1, 0
	s_and_b64 s[0:1], s[0:1], s[2:3]
	s_andn2_b64 vcc, exec, s[0:1]
	s_cbranch_vccnz .LBB0_2348
	s_add_u32 s0, s96, 0x4c00000
	s_addc_u32 s1, s97, 0
	s_add_u32 s2, s96, 0x8c00000
	s_addc_u32 s3, s97, 0
	s_add_u32 s4, s96, 0x100000
	s_addc_u32 s5, s97, 0
	s_add_u32 s12, s96, 0x180000
	s_addc_u32 s13, s97, 0
	v_readfirstlane_b32 s6, v192
	s_nop 3
	s_cmp_ge_u32 s6, 0x100
	s_cbranch_scc0 .Lattn_prio_0
	s_setprio 2
.Lattn_prio_0:
	s_cmpk_eq_i32 s88, 0x100
	s_mov_b64 s[6:7], -1
	s_cbranch_scc1 .LBB0_2199
	s_cmpk_gt_i32 s67, 0x1ff
	s_cbranch_scc1 .LBB0_2198
	v_bfe_u32 v0, v192, 5, 1
	v_lshlrev_b32_e32 v2, 3, v0
	v_lshlrev_b32_e32 v4, 2, v0
	v_lshlrev_b32_e32 v156, 4, v0
	v_lshrrev_b32_e32 v0, 2, v192
	v_lshlrev_b32_e32 v3, 3, v192
	v_and_or_b32 v0, v0, 3, v4
	v_and_b32_e32 v154, 24, v3
	v_lshlrev_b32_e32 v197, 6, v0
	v_and_b32_e32 v0, 16, v192
	v_lshlrev_b32_e32 v3, 2, v192
	v_and_or_b32 v0, v3, 12, v0
	v_lshlrev_b32_e32 v218, 1, v0
	v_mbcnt_lo_u32_b32 v0, -1, 0
	v_mbcnt_hi_u32_b32 v0, -1, v0
	v_and_b32_e32 v5, 64, v0
	v_xor_b32_e32 v3, 32, v0
	v_add_u32_e32 v5, 64, v5
	v_cmp_lt_i32_e32 vcc, v3, v5
	v_mov_b32_e32 v1, 0
	v_and_b32_e32 v152, 31, v192
	v_cndmask_b32_e32 v0, v0, v3, vcc
	v_lshlrev_b32_e32 v219, 2, v0
	v_and_b32_e32 v0, 3, v192
	v_lshlrev_b32_e32 v0, 4, v0
	v_mov_b32_e32 v157, v1
	v_lshl_add_u64 v[6:7], s[96:97], 0, v[0:1]
	s_mov_b64 s[6:7], 0x8d60400
	v_lshlrev_b32_e32 v164, 1, v2
	v_and_b32_e32 v153, 63, v192
	v_mul_u32_u24_e32 v155, 0xd0, v152
	s_mov_b32 s15, 0
	v_lshl_add_u64 v[158:159], s[4:5], 0, v[156:157]
	v_lshl_add_u64 v[160:161], s[12:13], 0, v[156:157]
	v_lshl_add_u64 v[162:163], v[6:7], 0, s[6:7]
	v_mov_b32_e32 v166, v164
	v_mov_b32_e32 v167, v1
	s_mov_b32 s9, 0x4ec4ec4f
	s_mov_b64 s[16:17], 0x580
	s_movk_i32 s33, 0x2c00
	s_mov_b64 s[18:19], 0xc00
	s_mov_b64 s[20:21], 0x400
	s_mov_b32 s36, 0x41000000
	s_mov_b64 s[22:23], 0x160000
	v_lshlrev_b32_e32 v168, 1, v4
	v_mov_b32_e32 v157, 0x2c00
	s_mov_b32 s37, s67
	s_mov_b32 s38, s67
	s_branch .LBB0_2106

; #define LAS __attribute__((address_space(3)))
; __device__ __forceinline__ void a2_qk(const LAS unsigned char* kb, const bf16x8 (&qf)[6], const f32x16& cneg, f32x16& st0, f32x16& st1) {
;     { const bf16x8 a0 = *(const LAS bf16x8*)(kb), a1 = *(const LAS bf16x8*)(kb + 32 * AT_KROW);
;       st0 = __builtin_amdgcn_mfma_f32_32x32x16_bf16(a0, qf[0], cneg, 0, 0, 0); st1 = __builtin_amdgcn_mfma_f32_32x32x16_bf16(a1, qf[0], cneg, 0, 0, 0); }
; #pragma unroll
;     for (int s = 1; s < 6; ++s) { const bf16x8 a0 = *(const LAS bf16x8*)(kb + s * 32), a1 = *(const LAS bf16x8*)(kb + 32 * AT_KROW + s * 32);
;         st0 = __builtin_amdgcn_mfma_f32_32x32x16_bf16(a0, qf[s], st0, 0, 0, 0); st1 = __builtin_amdgcn_mfma_f32_32x32x16_bf16(a1, qf[s], st1, 0, 0, 0); }
; }
; __device__ __forceinline__ float a2_max(const f32x16& st0, const f32x16& st1) {
;     float mt = fmaxf(st0[0], st1[0]);
; #pragma unroll
;     for (int r = 1; r < 16; ++r) mt = fmaxf(fmaxf(mt, st0[r]), st1[r]);
;     return fmaxf(mt, __shfl_xor(mt, 32));
; }
; __device__ __forceinline__ void attn2_unit(bf16_t* Z, const bf16_t* Hb, const float* rc, const float* rs, LAS unsigned char* lds, int b, int h, int qblk) {
;     ...
;         if (2 * kp + 1 <= cw) {
;             f32x16 sa0, sa1, sb0, sb1; bf16x8 pa[4], pb[4];
;             __builtin_amdgcn_s_setprio(1);
;             a2_qk(kb, qf, cneg, sa0, sa1);
;             a2_qk(kb + 64 * AT_KROW, qf, cneg, sb0, sb1);
;             __builtin_amdgcn_s_setprio(0);
;             const float mt = fmaxf(a2_max(sa0, sa1), a2_max(sb0, sb1));
;             if (kp == 0 || __builtin_amdgcn_ballot_w64(mt > 8.f) != 0ull) {
.LBB0_2235:
	s_andn2_b64 vcc, exec, s[6:7]
	s_cbranch_vccnz .LBB0_2244
	v_add_u32_e32 v0, v3, v156
	ds_read_b128 v[4:7], v0
	ds_read_b128 v[8:11], v0 offset:32
	v_mov_b64_e32 v[94:95], v[62:63]
	v_mov_b64_e32 v[92:93], v[60:61]
	v_mov_b64_e32 v[90:91], v[58:59]
	s_waitcnt lgkmcnt(0)
	v_mfma_f32_32x32x16_bf16 v[112:127], v[4:7], v[128:131], v[48:63]
	ds_read_b128 v[4:7], v0 offset:6656
	ds_read_b128 v[12:15], v0 offset:6688
	v_mov_b64_e32 v[88:89], v[56:57]
	v_mov_b64_e32 v[86:87], v[54:55]
	v_mov_b64_e32 v[84:85], v[52:53]
	v_mov_b64_e32 v[82:83], v[50:51]
	v_mov_b64_e32 v[80:81], v[48:49]
	s_waitcnt lgkmcnt(0)
	v_mfma_f32_32x32x16_bf16 v[96:111], v[4:7], v[128:131], v[48:63]
	v_mfma_f32_32x32x16_bf16 v[112:127], v[8:11], v[132:135], v[112:127]
	ds_read_b128 v[4:7], v0 offset:64
	ds_read_b128 v[8:11], v0 offset:96
	v_mfma_f32_32x32x16_bf16 v[96:111], v[12:15], v[132:135], v[96:111]
	s_waitcnt lgkmcnt(0)
	v_mfma_f32_32x32x16_bf16 v[112:127], v[4:7], v[136:139], v[112:127]
	ds_read_b128 v[4:7], v0 offset:6720
	ds_read_b128 v[12:15], v0 offset:6752
	s_waitcnt lgkmcnt(0)
	v_mfma_f32_32x32x16_bf16 v[96:111], v[4:7], v[136:139], v[96:111]
	v_mfma_f32_32x32x16_bf16 v[112:127], v[8:11], v[140:143], v[112:127]
	ds_read_b128 v[4:7], v0 offset:128
	ds_read_b128 v[8:11], v0 offset:160
	v_mfma_f32_32x32x16_bf16 v[96:111], v[12:15], v[140:143], v[96:111]
	s_waitcnt lgkmcnt(0)
	v_mfma_f32_32x32x16_bf16 v[112:127], v[4:7], v[144:147], v[112:127]
	ds_read_b128 v[4:7], v0 offset:6784
	ds_read_b128 v[12:15], v0 offset:6816
	s_waitcnt lgkmcnt(0)
	v_mfma_f32_32x32x16_bf16 v[96:111], v[4:7], v[144:147], v[96:111]
	v_mfma_f32_32x32x16_bf16 v[112:127], v[8:11], v[148:151], v[112:127]
	ds_read_b128 v[4:7], v0 offset:13312
	ds_read_b128 v[8:11], v0 offset:13344
	s_waitcnt lgkmcnt(0)
	v_mfma_f32_32x32x16_bf16 v[64:79], v[4:7], v[128:131], v[48:63]
	ds_read_b128 v[4:7], v0 offset:19968
	v_mfma_f32_32x32x16_bf16 v[96:111], v[12:15], v[148:151], v[96:111]
	ds_read_b128 v[12:15], v0 offset:20000
	s_waitcnt lgkmcnt(0)
	v_mfma_f32_32x32x16_bf16 v[80:95], v[4:7], v[128:131], v[80:95]
	v_mfma_f32_32x32x16_bf16 v[64:79], v[8:11], v[132:135], v[64:79]
	ds_read_b128 v[4:7], v0 offset:13376
	ds_read_b128 v[8:11], v0 offset:13408
	v_mfma_f32_32x32x16_bf16 v[80:95], v[12:15], v[132:135], v[80:95]
	s_waitcnt lgkmcnt(0)
	v_mfma_f32_32x32x16_bf16 v[64:79], v[4:7], v[136:139], v[64:79]
	ds_read_b128 v[4:7], v0 offset:20032
	ds_read_b128 v[12:15], v0 offset:20064
	s_waitcnt lgkmcnt(0)
	v_mfma_f32_32x32x16_bf16 v[80:95], v[4:7], v[136:139], v[80:95]
	v_mfma_f32_32x32x16_bf16 v[64:79], v[8:11], v[140:143], v[64:79]
	ds_read_b128 v[4:7], v0 offset:13440
	ds_read_b128 v[8:11], v0 offset:13472
	v_mfma_f32_32x32x16_bf16 v[80:95], v[12:15], v[140:143], v[80:95]
	s_waitcnt lgkmcnt(0)
	v_mfma_f32_32x32x16_bf16 v[64:79], v[4:7], v[144:147], v[64:79]
	ds_read_b128 v[4:7], v0 offset:20096
	ds_read_b128 v[12:15], v0 offset:20128
	s_waitcnt lgkmcnt(0)
	v_mfma_f32_32x32x16_bf16 v[80:95], v[4:7], v[144:147], v[80:95]
	v_mfma_f32_32x32x16_bf16 v[64:79], v[8:11], v[148:151], v[64:79]
	v_mfma_f32_32x32x16_bf16 v[80:95], v[12:15], v[148:151], v[80:95]
	v_max_f32_e32 v0, v96, v96
	v_max_f32_e32 v3, v112, v112
	v_max_f32_e32 v0, v3, v0
	s_nop 7
	v_max_f32_e32 v3, v80, v80
	v_max_f32_e32 v4, v64, v64
	v_max_f32_e32 v3, v4, v3
	v_max3_f32 v3, v3, v65, v81
	v_max3_f32 v3, v3, v66, v82
	v_max3_f32 v0, v0, v113, v97
	v_max3_f32 v3, v3, v67, v83
	v_max3_f32 v0, v0, v114, v98
	v_max3_f32 v3, v3, v68, v84
	v_max3_f32 v0, v0, v115, v99
	v_max3_f32 v3, v3, v69, v85
	v_max3_f32 v0, v0, v116, v100
	v_max3_f32 v3, v3, v70, v86
	v_max3_f32 v0, v0, v117, v101
	v_max3_f32 v3, v3, v71, v87
	v_max3_f32 v0, v0, v118, v102
	v_max3_f32 v3, v3, v72, v88
	v_max3_f32 v0, v0, v119, v103
	v_max3_f32 v3, v3, v73, v89
	v_max3_f32 v0, v0, v120, v104
	v_max3_f32 v3, v3, v74, v90
	v_max3_f32 v0, v0, v121, v105
	v_max3_f32 v3, v3, v75, v91
	v_max3_f32 v0, v0, v122, v106
	v_max3_f32 v3, v3, v76, v92
	v_max3_f32 v0, v0, v123, v107
	v_max3_f32 v3, v3, v77, v93
	v_max3_f32 v0, v0, v124, v108
	v_max3_f32 v3, v3, v78, v94
	v_max3_f32 v3, v3, v79, v95
	v_max3_f32 v0, v0, v125, v109
	ds_bpermute_b32 v4, v219, v3
	v_max3_f32 v0, v0, v126, v110
	v_max3_f32 v0, v0, v127, v111
	ds_bpermute_b32 v5, v219, v0
	s_cmp_eq_u32 s47, 1
	s_waitcnt lgkmcnt(0)
	v_max_f32_e32 v4, v4, v4
	v_max_f32_e32 v3, v3, v4
	s_cselect_b64 s[30:31], -1, 0
	s_cmp_lg_u32 s47, 1
	v_max3_f32 v3, v0, v5, v3
	s_cbranch_scc0 .LBB0_2246
	v_cmp_lt_f32_e32 vcc, s41, v3
	s_mov_b64 s[24:25], 0
	s_mov_b64 s[6:7], 0
	s_cbranch_vccz .LBB0_2239
	v_max_f32_e32 v0, v3, v3
	v_max_f32_e32 v0, 0, v0
	s_mov_b64 s[6:7], -1

; #define LAS __attribute__((address_space(3)))
; __device__ __forceinline__ void a2_qk(const LAS unsigned char* kb, const bf16x8 (&qf)[6], const f32x16& cneg, f32x16& st0, f32x16& st1) {
;     { const bf16x8 a0 = *(const LAS bf16x8*)(kb), a1 = *(const LAS bf16x8*)(kb + 32 * AT_KROW);
;       st0 = __builtin_amdgcn_mfma_f32_32x32x16_bf16(a0, qf[0], cneg, 0, 0, 0); st1 = __builtin_amdgcn_mfma_f32_32x32x16_bf16(a1, qf[0], cneg, 0, 0, 0); }
; #pragma unroll
;     for (int s = 1; s < 6; ++s) { const bf16x8 a0 = *(const LAS bf16x8*)(kb + s * 32), a1 = *(const LAS bf16x8*)(kb + 32 * AT_KROW + s * 32);
;         st0 = __builtin_amdgcn_mfma_f32_32x32x16_bf16(a0, qf[s], st0, 0, 0, 0); st1 = __builtin_amdgcn_mfma_f32_32x32x16_bf16(a1, qf[s], st1, 0, 0, 0); }
; }
; __device__ __forceinline__ float a2_max(const f32x16& st0, const f32x16& st1) {
;     float mt = fmaxf(st0[0], st1[0]);
; #pragma unroll
;     for (int r = 1; r < 16; ++r) mt = fmaxf(fmaxf(mt, st0[r]), st1[r]);
;     return fmaxf(mt, __shfl_xor(mt, 32));
; }
; __device__ __forceinline__ void attn2_unit(bf16_t* Z, const bf16_t* Hb, const float* rc, const float* rs, LAS unsigned char* lds, int b, int h, int qblk) {
;     ...
;         if (2 * kp + 1 <= cw) {
;             f32x16 sa0, sa1, sb0, sb1; bf16x8 pa[4], pb[4];
;             __builtin_amdgcn_s_setprio(1);
;             a2_qk(kb, qf, cneg, sa0, sa1);
;             a2_qk(kb + 64 * AT_KROW, qf, cneg, sb0, sb1);
;             __builtin_amdgcn_s_setprio(0);
;             const float mt = fmaxf(a2_max(sa0, sa1), a2_max(sb0, sb1));
;             if (kp == 0 || __builtin_amdgcn_ballot_w64(mt > 8.f) != 0ull) {
.LBB0_2281:
	s_andn2_b64 vcc, exec, s[6:7]
	s_cbranch_vccnz .LBB0_2290
	v_add_u32_e32 v0, v3, v156
	ds_read_b128 v[4:7], v0
	ds_read_b128 v[8:11], v0 offset:32
	v_mov_b64_e32 v[94:95], v[62:63]
	v_mov_b64_e32 v[92:93], v[60:61]
	v_mov_b64_e32 v[90:91], v[58:59]
	s_waitcnt lgkmcnt(0)
	v_mfma_f32_32x32x16_bf16 v[112:127], v[4:7], v[128:131], v[48:63]
	ds_read_b128 v[4:7], v0 offset:6656
	ds_read_b128 v[12:15], v0 offset:6688
	v_mov_b64_e32 v[88:89], v[56:57]
	v_mov_b64_e32 v[86:87], v[54:55]
	v_mov_b64_e32 v[84:85], v[52:53]
	v_mov_b64_e32 v[82:83], v[50:51]
	v_mov_b64_e32 v[80:81], v[48:49]
	s_waitcnt lgkmcnt(0)
	v_mfma_f32_32x32x16_bf16 v[96:111], v[4:7], v[128:131], v[48:63]
	v_mfma_f32_32x32x16_bf16 v[112:127], v[8:11], v[132:135], v[112:127]
	ds_read_b128 v[4:7], v0 offset:64
	ds_read_b128 v[8:11], v0 offset:96
	v_mfma_f32_32x32x16_bf16 v[96:111], v[12:15], v[132:135], v[96:111]
	s_waitcnt lgkmcnt(0)
	v_mfma_f32_32x32x16_bf16 v[112:127], v[4:7], v[136:139], v[112:127]
	ds_read_b128 v[4:7], v0 offset:6720
	ds_read_b128 v[12:15], v0 offset:6752
	s_waitcnt lgkmcnt(0)
	v_mfma_f32_32x32x16_bf16 v[96:111], v[4:7], v[136:139], v[96:111]
	v_mfma_f32_32x32x16_bf16 v[112:127], v[8:11], v[140:143], v[112:127]
	ds_read_b128 v[4:7], v0 offset:128
	ds_read_b128 v[8:11], v0 offset:160
	v_mfma_f32_32x32x16_bf16 v[96:111], v[12:15], v[140:143], v[96:111]
	s_waitcnt lgkmcnt(0)
	v_mfma_f32_32x32x16_bf16 v[112:127], v[4:7], v[144:147], v[112:127]
	ds_read_b128 v[4:7], v0 offset:6784
	ds_read_b128 v[12:15], v0 offset:6816
	s_waitcnt lgkmcnt(0)
	v_mfma_f32_32x32x16_bf16 v[96:111], v[4:7], v[144:147], v[96:111]
	v_mfma_f32_32x32x16_bf16 v[112:127], v[8:11], v[148:151], v[112:127]
	ds_read_b128 v[4:7], v0 offset:13312
	ds_read_b128 v[8:11], v0 offset:13344
	s_waitcnt lgkmcnt(0)
	v_mfma_f32_32x32x16_bf16 v[64:79], v[4:7], v[128:131], v[48:63]
	ds_read_b128 v[4:7], v0 offset:19968
	v_mfma_f32_32x32x16_bf16 v[96:111], v[12:15], v[148:151], v[96:111]
	ds_read_b128 v[12:15], v0 offset:20000
	s_waitcnt lgkmcnt(0)
	v_mfma_f32_32x32x16_bf16 v[80:95], v[4:7], v[128:131], v[80:95]
	v_mfma_f32_32x32x16_bf16 v[64:79], v[8:11], v[132:135], v[64:79]
	ds_read_b128 v[4:7], v0 offset:13376
	ds_read_b128 v[8:11], v0 offset:13408
	v_mfma_f32_32x32x16_bf16 v[80:95], v[12:15], v[132:135], v[80:95]
	s_waitcnt lgkmcnt(0)
	v_mfma_f32_32x32x16_bf16 v[64:79], v[4:7], v[136:139], v[64:79]
	ds_read_b128 v[4:7], v0 offset:20032
	ds_read_b128 v[12:15], v0 offset:20064
	s_waitcnt lgkmcnt(0)
	v_mfma_f32_32x32x16_bf16 v[80:95], v[4:7], v[136:139], v[80:95]
	v_mfma_f32_32x32x16_bf16 v[64:79], v[8:11], v[140:143], v[64:79]
	ds_read_b128 v[4:7], v0 offset:13440
	ds_read_b128 v[8:11], v0 offset:13472
	v_mfma_f32_32x32x16_bf16 v[80:95], v[12:15], v[140:143], v[80:95]
	s_waitcnt lgkmcnt(0)
	v_mfma_f32_32x32x16_bf16 v[64:79], v[4:7], v[144:147], v[64:79]
	ds_read_b128 v[4:7], v0 offset:20096
	ds_read_b128 v[12:15], v0 offset:20128
	s_waitcnt lgkmcnt(0)
	v_mfma_f32_32x32x16_bf16 v[80:95], v[4:7], v[144:147], v[80:95]
	v_mfma_f32_32x32x16_bf16 v[64:79], v[8:11], v[148:151], v[64:79]
	v_mfma_f32_32x32x16_bf16 v[80:95], v[12:15], v[148:151], v[80:95]
	v_max_f32_e32 v0, v96, v96
	v_max_f32_e32 v3, v112, v112
	v_max_f32_e32 v0, v3, v0
	s_nop 7
	v_max_f32_e32 v3, v80, v80
	v_max_f32_e32 v4, v64, v64
	v_max_f32_e32 v3, v4, v3
	v_max3_f32 v3, v3, v65, v81
	v_max3_f32 v3, v3, v66, v82
	v_max3_f32 v0, v0, v113, v97
	v_max3_f32 v3, v3, v67, v83
	v_max3_f32 v0, v0, v114, v98
	v_max3_f32 v3, v3, v68, v84
	v_max3_f32 v0, v0, v115, v99
	v_max3_f32 v3, v3, v69, v85
	v_max3_f32 v0, v0, v116, v100
	v_max3_f32 v3, v3, v70, v86
	v_max3_f32 v0, v0, v117, v101
	v_max3_f32 v3, v3, v71, v87
	v_max3_f32 v0, v0, v118, v102
	v_max3_f32 v3, v3, v72, v88
	v_max3_f32 v0, v0, v119, v103
	v_max3_f32 v3, v3, v73, v89
	v_max3_f32 v0, v0, v120, v104
	v_max3_f32 v3, v3, v74, v90
	v_max3_f32 v0, v0, v121, v105
	v_max3_f32 v3, v3, v75, v91
	v_max3_f32 v0, v0, v122, v106
	v_max3_f32 v3, v3, v76, v92
	v_max3_f32 v0, v0, v123, v107
	v_max3_f32 v3, v3, v77, v93
	v_max3_f32 v0, v0, v124, v108
	v_max3_f32 v3, v3, v78, v94
	v_max3_f32 v3, v3, v79, v95
	v_max3_f32 v0, v0, v125, v109
	ds_bpermute_b32 v4, v219, v3
	v_max3_f32 v0, v0, v126, v110
	v_max3_f32 v0, v0, v127, v111
	ds_bpermute_b32 v5, v219, v0
	s_cmp_eq_u32 s31, 1
	s_waitcnt lgkmcnt(0)
	v_max_f32_e32 v4, v4, v4
	v_max_f32_e32 v3, v3, v4
	s_cselect_b64 s[26:27], -1, 0
	s_cmp_lg_u32 s31, 1
	v_max3_f32 v3, v0, v5, v3
	s_cbranch_scc0 .LBB0_2292
	v_cmp_lt_f32_e32 vcc, s41, v3
	s_mov_b64 s[24:25], 0
	s_mov_b64 s[6:7], 0
	s_cbranch_vccz .LBB0_2285
	v_max_f32_e32 v0, v3, v3
	v_max_f32_e32 v0, 0, v0
	s_mov_b64 s[6:7], -1

; __device__ __forceinline__ unsigned xb_ld(unsigned* p)              { return __hip_atomic_load(p, __ATOMIC_RELAXED, __HIP_MEMORY_SCOPE_AGENT); }
; __device__ __forceinline__ void xcd_barrier_complete(unsigned* bar, unsigned x, unsigned& nloc, unsigned& nx) {
;     const unsigned G = gridDim.x * gridDim.y * gridDim.z;
;     unsigned sum, cnt, mine, sp = 0u;
;     for (;;) {
;         sum = 0u; cnt = 0u; mine = 0u;
; #pragma unroll
;         for (unsigned j = 0; j < 16; ++j) { const unsigned c = xb_ld(&bar[XB_XCNT(j)]); sum += c; cnt += (c > 0u) ? 1u : 0u; mine = (j == x) ? c : mine; }
; __device__ __forceinline__ void xcd_barrier(const XcdBarrier& b) {
;     asm volatile("s_waitcnt vmcnt(0)" ::: "memory");
;     __syncthreads();
;     if (threadIdx.x == 0) {
;         unsigned* bar = b.bar;
;         __builtin_amdgcn_s_waitcnt(0);
;         unsigned nloc = b.st[0], nx = b.st[1];
;         if (nloc == 0u) { xcd_barrier_complete(bar, b.x, nloc, nx); b.st[0] = nloc; b.st[1] = nx; }
.LBB0_2294:
	s_setprio 0
	v_readlane_b32 s4, v246, 12
	v_readlane_b32 s5, v246, 13
	s_cmp_lt_i32 s5, 19
	s_cbranch_scc1 .LBB0_2348
	s_waitcnt vmcnt(0)
	s_waitcnt vmcnt(0)
	s_barrier
	s_mov_b64 s[0:1], exec
	v_readlane_b32 s2, v246, 10
	v_readlane_b32 s3, v246, 11
	s_and_b64 s[2:3], s[0:1], s[2:3]
	s_mov_b64 exec, s[2:3]
	s_cbranch_execz .LBB0_2347
	s_add_i32 s2, 0, 0x23ff0
	v_mov_b32_e32 v0, s2
	s_waitcnt vmcnt(0) expcnt(0) lgkmcnt(0)
	ds_read_b32 v2, v0
	s_add_i32 s2, 0, 0x23ff4
	v_mov_b32_e32 v0, s2
	ds_read_b32 v0, v0
	s_waitcnt lgkmcnt(1)
	v_cmp_ne_u32_e32 vcc, 0, v2
	s_cbranch_vccnz .LBB0_2311
	s_add_u32 s2, s96, 0x80200
	s_addc_u32 s3, s97, 0
	s_add_u32 s4, s96, 0x80400
	s_addc_u32 s5, s97, 0
	s_add_u32 s6, s96, 0x80500
	s_addc_u32 s7, s97, 0
	s_add_u32 s12, s96, 0x80600
	s_addc_u32 s13, s97, 0
	s_add_u32 s14, s96, 0x80700
	s_addc_u32 s15, s97, 0
	s_add_u32 s16, s96, 0x80800
	s_addc_u32 s17, s97, 0
	s_add_u32 s18, s96, 0x80900
	s_addc_u32 s19, s97, 0
	s_add_u32 s20, s96, 0x80a00
	s_addc_u32 s21, s97, 0
	s_add_u32 s22, s96, 0x80b00
	s_addc_u32 s23, s97, 0
	s_add_u32 s24, s96, 0x80c00
	s_addc_u32 s25, s97, 0
	s_add_u32 s26, s96, 0x80d00
	s_addc_u32 s27, s97, 0
	s_add_u32 s28, s96, 0x80e00
	s_addc_u32 s29, s97, 0
	s_add_u32 s30, s96, 0x80f00
	s_addc_u32 s31, s97, 0
	s_add_u32 s34, s96, 0x81000
	s_addc_u32 s35, s97, 0
	s_add_u32 s36, s96, 0x81100
	s_addc_u32 s37, s97, 0
	s_add_u32 s38, s96, 0x81200
	s_addc_u32 s39, s97, 0
	s_mul_i32 s9, s89, s84
	s_add_u32 s40, s96, 0x81300
	s_mul_i32 s9, s9, s88
	s_addc_u32 s41, s97, 0
	s_mov_b32 s33, 1
	v_mov_b32_e32 v16, 0
	s_branch .LBB0_2299
